# combined: destructive first-set-bit block search + de-serialised NSA tile epilogue + top-16 early exit, on the LDS-DMA/ILP SEL loop
# speedup vs baseline: 1.0144x; 1.0144x over previous
.LBB0_1620:
	s_and_b64 vcc, exec, s[0:1]
	s_cbranch_vccnz .LBB0_1655
	v_lshrrev_b32_e32 v7, 3, v3
	v_ashrrev_i32_e32 v6, 2, v3
	v_and_b32_e32 v7, 12, v7
	v_lshlrev_b32_e32 v9, 2, v3
	v_and_or_b32 v7, v6, 3, v7
	v_lshlrev_b32_e32 v6, 4, v6
	v_and_b32_e32 v10, 12, v9
	v_bitop3_b32 v11, v7, v6, v10 bitop3:0xde
	v_lshlrev_b32_e32 v177, 4, v11
	v_or_b32_e32 v11, 1, v10
	v_bitop3_b32 v11, v11, v6, v7 bitop3:0xde
	v_lshlrev_b32_e32 v178, 4, v11
	v_or_b32_e32 v11, 2, v10
	v_or_b32_e32 v10, 3, v10
	v_bfe_u32 v8, v3, 2, 3
	v_bitop3_b32 v11, v11, v6, v7 bitop3:0xde
	v_bitop3_b32 v6, v10, v6, v7 bitop3:0xde
	v_lshlrev_b32_e32 v180, 4, v6
	v_and_b32_e32 v6, -8, v9
	v_and_b32_e32 v7, 4, v9
	v_bitop3_b32 v9, v9, v8, 4 bitop3:0x6c
	v_or_b32_e32 v9, v9, v6
	v_lshlrev_b32_e32 v181, 4, v9
	v_bitop3_b32 v9, v7, v8, 1 bitop3:0x36
	v_or_b32_e32 v9, v9, v6
	v_lshlrev_b32_e32 v182, 4, v9
	v_bitop3_b32 v9, v7, v8, 2 bitop3:0x36
	v_bitop3_b32 v7, v7, v8, 3 bitop3:0x36
	v_mov_b64_e32 v[0:1], v[252:253]
	v_and_b32_e32 v5, 15, v3
	v_lshrrev_b32_e32 v4, 4, v4
	v_or_b32_e32 v9, v9, v6
	v_or_b32_e32 v6, v7, v6
	v_lshl_add_u64 v[164:165], s[18:19], 0, v[0:1]
	v_lshl_add_u64 v[166:167], s[20:21], 0, v[0:1]
	v_ashrrev_i32_e32 v0, 3, v3
	v_lshlrev_b32_e32 v183, 4, v9
	v_lshlrev_b32_e32 v184, 4, v6
	v_and_b32_e32 v185, -8, v0
	v_and_b32_e32 v1, 12, v3
	v_bitop3_b32 v6, v4, v3, 15 bitop3:0x78
	v_bitop3_b32 v7, v4, v5, 4 bitop3:0x36
	v_bitop3_b32 v8, v4, v5, 8 bitop3:0x36
	v_bitop3_b32 v9, v4, v5, 12 bitop3:0x36
	v_bfe_u32 v0, v3, 2, 2
	v_add_lshl_u32 v1, v1, v5, 8
	v_lshlrev_b32_e32 v6, 4, v6
	v_lshlrev_b32_e32 v7, 4, v7
	v_lshlrev_b32_e32 v8, 4, v8
	v_lshlrev_b32_e32 v9, 4, v9
	v_add_u32_e32 v199, s77, v185
	v_lshlrev_b32_e64 v186, v0, 1
	v_or_b32_e32 v187, v6, v1
	v_or_b32_e32 v189, v7, v1
	v_or_b32_e32 v191, v8, v1
	v_or_b32_e32 v193, v9, v1
	v_or_b32_e32 v1, 0x2000, v1
	v_or_b32_e32 v200, v199, v0
	v_bfe_u32 v0, v3, 1, 3
	v_mov_b32_e32 v18, v17
	v_mov_b32_e32 v19, v17
	v_or3_b32 v195, v6, v1, s8
	v_or3_b32 v196, v7, v1, s8
	v_or3_b32 v197, v8, v1, s8
	v_or3_b32 v198, v9, v1, s8
	v_xor_b32_e32 v1, v4, v0
	v_bitop3_b32 v0, v4, v0, 4 bitop3:0x36
	v_mov_b32_e32 v16, v17
	v_mov_b64_e32 v[54:55], v[18:19]
	v_mov_b64_e32 v[58:59], v[18:19]
	v_mov_b64_e32 v[62:63], v[18:19]
	v_mov_b64_e32 v[66:67], v[18:19]
	v_mov_b64_e32 v[70:71], v[18:19]
	v_mov_b64_e32 v[74:75], v[18:19]
	v_mov_b64_e32 v[78:79], v[18:19]
	v_mov_b64_e32 v[82:83], v[18:19]
	v_mov_b64_e32 v[86:87], v[18:19]
	v_mov_b64_e32 v[90:91], v[18:19]
	v_mov_b64_e32 v[94:95], v[18:19]
	v_mov_b64_e32 v[98:99], v[18:19]
	v_mov_b64_e32 v[102:103], v[18:19]
	v_mov_b64_e32 v[106:107], v[18:19]
	v_mov_b64_e32 v[110:111], v[18:19]
	v_mov_b64_e32 v[114:115], v[18:19]
	v_lshlrev_b32_e32 v179, 4, v11
	v_or_b32_e32 v188, 0x400, v187
	v_or_b32_e32 v190, 0x400, v189
	v_or_b32_e32 v192, 0x400, v191
	v_or_b32_e32 v194, 0x400, v193
	v_lshlrev_b32_e32 v201, 3, v4
	v_lshlrev_b32_e32 v202, 7, v5
	v_lshlrev_b32_e32 v203, 4, v1
	v_lshlrev_b32_e32 v204, 4, v0
	v_or_b32_e32 v205, 4, v200
	v_mov_b32_e32 v175, 0
	v_mov_b32_e32 v206, 0xf149f2ca
	v_mov_b64_e32 v[52:53], v[16:17]
	v_mov_b64_e32 v[56:57], v[16:17]
	v_mov_b64_e32 v[60:61], v[16:17]
	v_mov_b64_e32 v[64:65], v[16:17]
	v_mov_b64_e32 v[68:69], v[16:17]
	v_mov_b64_e32 v[72:73], v[16:17]
	v_mov_b64_e32 v[76:77], v[16:17]
	v_mov_b64_e32 v[80:81], v[16:17]
	v_mov_b64_e32 v[84:85], v[16:17]
	v_mov_b64_e32 v[88:89], v[16:17]
	v_mov_b64_e32 v[92:93], v[16:17]
	v_mov_b64_e32 v[96:97], v[16:17]
	v_mov_b64_e32 v[100:101], v[16:17]
	v_mov_b64_e32 v[104:105], v[16:17]
	v_mov_b64_e32 v[108:109], v[16:17]
	v_mov_b64_e32 v[112:113], v[16:17]
	v_mov_b32_e32 v18, 0xf149f2ca
	v_mov_b32_e32 v176, 0
	s_lshr_b32 s0, s94, 6
.Lsrch_init:
	s_cmp_eq_u32 s0, 0
	s_cbranch_scc1 .Lsrch_init_done
	s_mov_b64 s[10:11], s[12:13]
	s_mov_b64 s[12:13], s[14:15]
	s_mov_b64 s[14:15], s[16:17]
	s_mov_b64 s[16:17], 0
	s_sub_i32 s0, s0, 1
	s_branch .Lsrch_init
.Lsrch_init_done:
	s_and_b32 s0, s94, 63
	s_bitset0_b64 s[10:11], s0
.LBB0_1622:
	s_and_b32 s95, s94, 0xc0
	s_cmp_lg_u64 s[10:11], 0
	s_cbranch_scc1 .Lsrch_found_a
.Lsrch_shift_a:
	s_add_i32 s95, s95, 64
	s_mov_b64 s[10:11], s[12:13]
	s_mov_b64 s[12:13], s[14:15]
	s_mov_b64 s[14:15], s[16:17]
	s_mov_b64 s[16:17], 0
	s_cmpk_gt_u32 s95, 0xff
	s_cbranch_scc1 .LBB0_1632
	s_cmp_lg_u64 s[10:11], 0
	s_cbranch_scc0 .Lsrch_shift_a
.Lsrch_found_a:
	s_ff1_i32_b64 s0, s[10:11]
	s_bitset0_b64 s[10:11], s0
	s_or_b32 s95, s95, s0

.Lselb_1652:
	s_or_b64 exec, exec, s[80:81]
	s_andn2_b64 vcc, exec, s[78:79]
	s_cbranch_vccz .Lsel_exit
	s_waitcnt lgkmcnt(0)
	v_mov_b32_e32 v2, v19
	s_mov_b32 s94, s95
	s_branch .LBB0_1622
.Lsel_exit:
	s_waitcnt vmcnt(0) lgkmcnt(0)
	s_barrier
	s_branch .LBB0_1656
